# compress MLP first GEMM: W1 fragment loads ring-buffered 16 deep instead of one load+wait per MFMA
# speedup vs baseline: 1.0180x; 1.0180x over previous
; #define LAS __attribute__((address_space(3)))
; #define MFMA32(a, b, c) __builtin_amdgcn_mfma_f32_32x32x16_bf16((a), (b), (c), 0, 0, 0)
; __device__ __forceinline__ void compress_item(const CmpArgs& A, int item, LAS unsigned char* lds, int tid) {
;     ...
;     const bf16_t* wf = A.w1t + (size_t)kv * 256 * 2048 + ((size_t)w * 128 * 64 + lane) * 8;
;     f32x16 acc;
; #pragma unroll
;     for (int i = 0; i < 16; ++i) acc[i] = 0.f;
; #pragma unroll 8
;     for (int pos = 0; pos < 32; ++pos) { const int t = 16 * r + pos; LAS const unsigned char* arow = lds + (t ^ ((t >> 7) & 1)) * 128; const int sw = (t >> 4) & 7;
; #pragma unroll
;         for (int q = 0; q < 4; ++q) { const bf16x8 af = *(LAS const bf16x8*)(arow + (((2 * q + hh) ^ sw) * 16)), bfr = *(const bf16x8*)(wf + (size_t)(4 * pos + q) * 512); acc = MFMA32(af, bfr, acc); } }
.LBB0_929:
	s_or_b64 exec, exec, s[0:1]
	s_ashr_i32 s0, s14, 6
	s_ashr_i32 s8, s26, 6
	s_ashr_i32 s1, s0, 31
	s_ashr_i32 s9, s8, 31
	s_lshl_b64 s[12:13], s[0:1], 20
	s_lshl_b64 s[24:25], s[8:9], 17
	s_add_u32 s9, s12, s24
	s_addc_u32 s13, s13, s25
	v_readlane_b32 s12, v255, 20
	v_and_b32_e32 v38, 31, v39
	v_and_b32_e32 v0, 63, v39
	v_bfe_u32 v39, v39, 5, 1
	s_add_u32 s12, s12, s9
	v_readlane_b32 s9, v255, 21
	s_waitcnt vmcnt(0)
	v_lshlrev_b32_e32 v19, 4, v38
	v_lshlrev_b32_e32 v18, 4, v39
	v_lshlrev_b32_e32 v0, 4, v0
	s_addc_u32 s13, s9, s13
	v_mov_b32_e32 v2, 0
	v_or_b32_e32 v24, 32, v18
	v_or_b32_e32 v25, 64, v18
	v_or_b32_e32 v26, 0x60, v18
	v_or_b32_e32 v27, 7, v19
	v_lshl_or_b32 v28, v38, 11, v216
	v_lshl_add_u64 v[20:21], s[12:13], 0, v[0:1]
	v_or_b32_e32 v0, 6, v19
	v_or_b32_e32 v29, 4, v19
	v_or_b32_e32 v30, 2, v19
	s_mov_b64 s[40:41], 0
	v_mov_b32_e32 v3, v2
	v_mov_b32_e32 v4, v2
	v_mov_b32_e32 v5, v2
	v_mov_b32_e32 v6, v2
	v_mov_b32_e32 v7, v2
	v_mov_b32_e32 v8, v2
	v_mov_b32_e32 v9, v2
	v_mov_b32_e32 v10, v2
	v_mov_b32_e32 v11, v2
	v_mov_b32_e32 v12, v2
	v_mov_b32_e32 v13, v2
	v_mov_b32_e32 v14, v2
	v_mov_b32_e32 v15, v2
	v_mov_b32_e32 v16, v2
	v_mov_b32_e32 v17, v2
	s_mov_b32 s98, 0x1f400000
	s_mov_b32 s99, 0
	v_lshl_add_u64 v[114:115], v[20:21], 0, s[98:99]
	s_movk_i32 s98, 0x1000
	global_load_dwordx4 v[50:53], v[114:115], off
	global_load_dwordx4 v[54:57], v[114:115], off offset:1024
	global_load_dwordx4 v[58:61], v[114:115], off offset:2048
	global_load_dwordx4 v[62:65], v[114:115], off offset:3072
	v_lshl_add_u64 v[114:115], v[114:115], 0, s[98:99]
	global_load_dwordx4 v[66:69], v[114:115], off
	global_load_dwordx4 v[70:73], v[114:115], off offset:1024
	global_load_dwordx4 v[74:77], v[114:115], off offset:2048
	global_load_dwordx4 v[78:81], v[114:115], off offset:3072
	v_lshl_add_u64 v[114:115], v[114:115], 0, s[98:99]
	global_load_dwordx4 v[82:85], v[114:115], off
	global_load_dwordx4 v[86:89], v[114:115], off offset:1024
	global_load_dwordx4 v[90:93], v[114:115], off offset:2048
	global_load_dwordx4 v[94:97], v[114:115], off offset:3072
	v_lshl_add_u64 v[114:115], v[114:115], 0, s[98:99]
	global_load_dwordx4 v[98:101], v[114:115], off
	global_load_dwordx4 v[102:105], v[114:115], off offset:1024
	global_load_dwordx4 v[106:109], v[114:115], off offset:2048
	global_load_dwordx4 v[110:113], v[114:115], off offset:3072
	v_lshl_add_u64 v[114:115], v[114:115], 0, s[98:99]
	s_waitcnt lgkmcnt(0)
	s_barrier
.LBB0_930:
	v_add_u32_e32 v49, -7, v27
	v_and_b32_e32 v33, 0x80, v19
	v_bitop3_b32 v22, v49, v18, s35 bitop3:0x6c
	v_or_b32_e32 v22, v22, v33
	v_add_u32_e32 v22, 0, v22
	v_add3_u32 v22, v22, v28, s10
	ds_read_b128 v[34:37], v22
	s_nop 0
	s_nop 0
	v_and_b32_e32 v48, 0x80, v30
	v_and_b32_e32 v32, 0x80, v29
	v_and_b32_e32 v31, 0x80, v0
	s_add_u32 s40, s40, 0x8000
	s_addc_u32 s41, s41, 0
	v_add_u32_e32 v0, 8, v0
	v_add_u32_e32 v29, 8, v29
	v_add_u32_e32 v19, 8, v19
	v_add_u32_e32 v30, 8, v30
	s_cmp_eq_u32 s40, 0x20000
	s_waitcnt vmcnt(15) lgkmcnt(0)
	v_mfma_f32_32x32x16_bf16 v[2:17], v[34:37], v[50:53], v[2:17]
	global_load_dwordx4 v[50:53], v[114:115], off
	v_bitop3_b32 v34, v49, v24, s35 bitop3:0x6c
	v_or_b32_e32 v34, v34, v33
	v_add_u32_e32 v34, 0, v34
	v_add3_u32 v34, v34, v28, s10
	ds_read_b128 v[34:37], v34
	s_waitcnt vmcnt(15) lgkmcnt(0)
	v_mfma_f32_32x32x16_bf16 v[2:17], v[34:37], v[54:57], v[2:17]
	global_load_dwordx4 v[54:57], v[114:115], off offset:1024
	v_bitop3_b32 v34, v49, v25, s35 bitop3:0x6c
	v_or_b32_e32 v34, v34, v33
	v_add_u32_e32 v34, 0, v34
	v_add3_u32 v34, v34, v28, s10
	ds_read_b128 v[34:37], v34
	s_waitcnt vmcnt(15) lgkmcnt(0)
	v_mfma_f32_32x32x16_bf16 v[2:17], v[34:37], v[58:61], v[2:17]
	global_load_dwordx4 v[58:61], v[114:115], off offset:2048
	v_bitop3_b32 v34, v49, v26, s35 bitop3:0x6c
	v_or_b32_e32 v33, v34, v33
	v_add_u32_e32 v33, 0, v33
	v_add3_u32 v33, v33, v28, s10
	ds_read_b128 v[34:37], v33
	v_add_u32_e32 v33, -6, v27
	s_waitcnt vmcnt(15) lgkmcnt(0)
	v_mfma_f32_32x32x16_bf16 v[2:17], v[34:37], v[62:65], v[2:17]
	global_load_dwordx4 v[62:65], v[114:115], off offset:3072
	v_lshl_add_u64 v[114:115], v[114:115], 0, s[98:99]
	v_add_u32_e32 v34, 0xfffffd00, v28
	v_and_b32_e32 v35, 0x80, v33
	v_xad_u32 v44, v35, v34, 0
	v_and_b32_e32 v33, 0x70, v33
	v_xad_u32 v34, v33, v18, v44
	ds_read_b128 v[34:37], v34
	s_waitcnt vmcnt(15) lgkmcnt(0)
	v_mfma_f32_32x32x16_bf16 v[2:17], v[34:37], v[66:69], v[2:17]
	global_load_dwordx4 v[66:69], v[114:115], off
	v_xad_u32 v34, v33, v24, v44
	ds_read_b128 v[34:37], v34
	s_waitcnt vmcnt(15) lgkmcnt(0)
	v_mfma_f32_32x32x16_bf16 v[2:17], v[34:37], v[70:73], v[2:17]
	global_load_dwordx4 v[70:73], v[114:115], off offset:1024
	v_xad_u32 v34, v33, v25, v44
	ds_read_b128 v[34:37], v34
	v_xad_u32 v33, v33, v26, v44
	s_nop 0
	s_waitcnt vmcnt(15) lgkmcnt(0)
	v_mfma_f32_32x32x16_bf16 v[2:17], v[34:37], v[74:77], v[2:17]
	global_load_dwordx4 v[74:77], v[114:115], off offset:2048
	ds_read_b128 v[34:37], v33
	v_add_u32_e32 v33, -5, v27
	s_nop 0
	s_waitcnt vmcnt(15) lgkmcnt(0)
	v_mfma_f32_32x32x16_bf16 v[2:17], v[34:37], v[78:81], v[2:17]
	global_load_dwordx4 v[78:81], v[114:115], off offset:3072
	v_lshl_add_u64 v[114:115], v[114:115], 0, s[98:99]
	v_bitop3_b32 v34, v33, v18, s35 bitop3:0x6c
	v_or_b32_e32 v34, v34, v48
	v_add_u32_e32 v34, 0, v34
	v_add3_u32 v34, v34, v28, s2
	ds_read_b128 v[34:37], v34
	s_waitcnt vmcnt(15) lgkmcnt(0)
	v_mfma_f32_32x32x16_bf16 v[2:17], v[34:37], v[82:85], v[2:17]
	global_load_dwordx4 v[82:85], v[114:115], off
	v_bitop3_b32 v34, v33, v24, s35 bitop3:0x6c
	v_or_b32_e32 v34, v34, v48
	v_add_u32_e32 v34, 0, v34
	v_add3_u32 v34, v34, v28, s2
	ds_read_b128 v[34:37], v34
	s_waitcnt vmcnt(15) lgkmcnt(0)
; #define LAS __attribute__((address_space(3)))
; #define MFMA32(a, b, c) __builtin_amdgcn_mfma_f32_32x32x16_bf16((a), (b), (c), 0, 0, 0)
; __device__ __forceinline__ void compress_item(const CmpArgs& A, int item, LAS unsigned char* lds, int tid) {
;     ...
; #pragma unroll 8
;     for (int pos = 0; pos < 32; ++pos) { const int t = 16 * r + pos; LAS const unsigned char* arow = lds + (t ^ ((t >> 7) & 1)) * 128; const int sw = (t >> 4) & 7;
; #pragma unroll
;         for (int q = 0; q < 4; ++q) { const bf16x8 af = *(LAS const bf16x8*)(arow + (((2 * q + hh) ^ sw) * 16)), bfr = *(const bf16x8*)(wf + (size_t)(4 * pos + q) * 512); acc = MFMA32(af, bfr, acc); } }
	v_mfma_f32_32x32x16_bf16 v[2:17], v[34:37], v[86:89], v[2:17]
	global_load_dwordx4 v[86:89], v[114:115], off offset:1024
	v_bitop3_b32 v34, v33, v25, s35 bitop3:0x6c
	v_or_b32_e32 v34, v34, v48
	v_add_u32_e32 v34, 0, v34
	v_add3_u32 v34, v34, v28, s2
	ds_read_b128 v[34:37], v34
	v_bitop3_b32 v33, v33, v26, s35 bitop3:0x6c
	v_or_b32_e32 v33, v33, v48
	v_add_u32_e32 v33, 0, v33
	v_add3_u32 v33, v33, v28, s2
	s_waitcnt vmcnt(15) lgkmcnt(0)
	v_mfma_f32_32x32x16_bf16 v[2:17], v[34:37], v[90:93], v[2:17]
	global_load_dwordx4 v[90:93], v[114:115], off offset:2048
	ds_read_b128 v[34:37], v33
	v_add_u32_e32 v33, -4, v27
	s_waitcnt vmcnt(15) lgkmcnt(0)
	v_mfma_f32_32x32x16_bf16 v[2:17], v[34:37], v[94:97], v[2:17]
	global_load_dwordx4 v[94:97], v[114:115], off offset:3072
	v_lshl_add_u64 v[114:115], v[114:115], 0, s[98:99]
	v_add_u32_e32 v34, 0xfffffe00, v28
	v_and_b32_e32 v35, 0x80, v33
	v_xad_u32 v44, v35, v34, 0
	v_and_b32_e32 v33, 0x70, v33
	v_xad_u32 v34, v33, v18, v44
	ds_read_b128 v[34:37], v34
	s_waitcnt vmcnt(15) lgkmcnt(0)
	v_mfma_f32_32x32x16_bf16 v[2:17], v[34:37], v[98:101], v[2:17]
	global_load_dwordx4 v[98:101], v[114:115], off
	v_xad_u32 v34, v33, v24, v44
	ds_read_b128 v[34:37], v34
	s_waitcnt vmcnt(15) lgkmcnt(0)
	v_mfma_f32_32x32x16_bf16 v[2:17], v[34:37], v[102:105], v[2:17]
	global_load_dwordx4 v[102:105], v[114:115], off offset:1024
	v_xad_u32 v34, v33, v25, v44
	ds_read_b128 v[34:37], v34
	v_xad_u32 v33, v33, v26, v44
	s_nop 0
	s_waitcnt vmcnt(15) lgkmcnt(0)
	v_mfma_f32_32x32x16_bf16 v[2:17], v[34:37], v[106:109], v[2:17]
	global_load_dwordx4 v[106:109], v[114:115], off offset:2048
	ds_read_b128 v[34:37], v33
	v_add_u32_e32 v33, -3, v27
	s_nop 0
	s_waitcnt vmcnt(15) lgkmcnt(0)
	v_mfma_f32_32x32x16_bf16 v[2:17], v[34:37], v[110:113], v[2:17]
	global_load_dwordx4 v[110:113], v[114:115], off offset:3072
	v_lshl_add_u64 v[114:115], v[114:115], 0, s[98:99]
	s_cmp_eq_u32 s40, 0x20000
	s_cbranch_scc1 .Lcmp_tail
	v_bitop3_b32 v34, v33, v18, s35 bitop3:0x6c
	v_or_b32_e32 v34, v34, v32
	v_add_u32_e32 v34, 0, v34
	v_add3_u32 v34, v34, v28, s11
	ds_read_b128 v[34:37], v34
	s_waitcnt vmcnt(15) lgkmcnt(0)
	v_mfma_f32_32x32x16_bf16 v[2:17], v[34:37], v[50:53], v[2:17]
	global_load_dwordx4 v[50:53], v[114:115], off
	v_bitop3_b32 v34, v33, v24, s35 bitop3:0x6c
	v_or_b32_e32 v34, v34, v32
	v_add_u32_e32 v34, 0, v34
	v_add3_u32 v34, v34, v28, s11
	ds_read_b128 v[34:37], v34
	s_waitcnt vmcnt(15) lgkmcnt(0)
	v_mfma_f32_32x32x16_bf16 v[2:17], v[34:37], v[54:57], v[2:17]
	global_load_dwordx4 v[54:57], v[114:115], off offset:1024
	v_bitop3_b32 v34, v33, v25, s35 bitop3:0x6c
	v_or_b32_e32 v34, v34, v32
	v_add_u32_e32 v34, 0, v34
	v_add3_u32 v34, v34, v28, s11
	ds_read_b128 v[34:37], v34
	v_bitop3_b32 v33, v33, v26, s35 bitop3:0x6c
	v_or_b32_e32 v32, v33, v32
	v_add_u32_e32 v32, 0, v32
	v_add3_u32 v32, v32, v28, s11
	s_waitcnt vmcnt(15) lgkmcnt(0)
	v_mfma_f32_32x32x16_bf16 v[2:17], v[34:37], v[58:61], v[2:17]
	global_load_dwordx4 v[58:61], v[114:115], off offset:2048
	ds_read_b128 v[32:35], v32
	v_add_u32_e32 v44, -1, v27
	s_waitcnt vmcnt(15) lgkmcnt(0)
	v_mfma_f32_32x32x16_bf16 v[2:17], v[32:35], v[62:65], v[2:17]
	global_load_dwordx4 v[62:65], v[114:115], off offset:3072
	v_lshl_add_u64 v[114:115], v[114:115], 0, s[98:99]
	v_add_u32_e32 v32, -2, v27
	v_add_u32_e32 v33, 0xffffff00, v28
	v_and_b32_e32 v34, 0x80, v32
	v_xad_u32 v36, v34, v33, 0
	v_and_b32_e32 v37, 0x70, v32
	v_xad_u32 v32, v37, v18, v36
	ds_read_b128 v[32:35], v32
	s_waitcnt vmcnt(15) lgkmcnt(0)
	v_mfma_f32_32x32x16_bf16 v[2:17], v[32:35], v[66:69], v[2:17]
	global_load_dwordx4 v[66:69], v[114:115], off
	v_xad_u32 v32, v37, v24, v36
	ds_read_b128 v[32:35], v32
	s_waitcnt vmcnt(15) lgkmcnt(0)
	v_mfma_f32_32x32x16_bf16 v[2:17], v[32:35], v[70:73], v[2:17]
	global_load_dwordx4 v[70:73], v[114:115], off offset:1024
	v_xad_u32 v32, v37, v25, v36
	ds_read_b128 v[32:35], v32
	s_waitcnt vmcnt(15) lgkmcnt(0)
	v_mfma_f32_32x32x16_bf16 v[2:17], v[32:35], v[74:77], v[2:17]
	global_load_dwordx4 v[74:77], v[114:115], off offset:2048
	v_xad_u32 v32, v37, v26, v36
	ds_read_b128 v[32:35], v32
	s_nop 0
	s_waitcnt vmcnt(15) lgkmcnt(0)
	v_mfma_f32_32x32x16_bf16 v[2:17], v[32:35], v[78:81], v[2:17]
	global_load_dwordx4 v[78:81], v[114:115], off offset:3072
	v_lshl_add_u64 v[114:115], v[114:115], 0, s[98:99]
	v_bitop3_b32 v32, v44, v18, s35 bitop3:0x6c
	v_or_b32_e32 v32, v32, v31
	v_add_u32_e32 v32, 0, v32
	v_add3_u32 v32, v32, v28, s3
	ds_read_b128 v[32:35], v32
	s_waitcnt vmcnt(15) lgkmcnt(0)
	v_mfma_f32_32x32x16_bf16 v[2:17], v[32:35], v[82:85], v[2:17]
	global_load_dwordx4 v[82:85], v[114:115], off
	v_bitop3_b32 v32, v44, v24, s35 bitop3:0x6c
	v_or_b32_e32 v32, v32, v31
	v_add_u32_e32 v32, 0, v32
	v_add3_u32 v32, v32, v28, s3
	ds_read_b128 v[32:35], v32
	s_waitcnt vmcnt(15) lgkmcnt(0)
	v_mfma_f32_32x32x16_bf16 v[2:17], v[32:35], v[86:89], v[2:17]
	global_load_dwordx4 v[86:89], v[114:115], off offset:1024
	v_bitop3_b32 v32, v44, v25, s35 bitop3:0x6c
	v_or_b32_e32 v32, v32, v31
	v_add_u32_e32 v32, 0, v32
	v_add3_u32 v32, v32, v28, s3
	ds_read_b128 v[32:35], v32
	s_waitcnt vmcnt(15) lgkmcnt(0)
	v_mfma_f32_32x32x16_bf16 v[2:17], v[32:35], v[90:93], v[2:17]
	global_load_dwordx4 v[90:93], v[114:115], off offset:2048
	v_bitop3_b32 v32, v44, v26, s35 bitop3:0x6c
	v_or_b32_e32 v31, v32, v31
	v_add_u32_e32 v31, 0, v31
	v_add3_u32 v31, v31, v28, s3
	ds_read_b128 v[32:35], v31
	v_and_b32_e32 v31, 0x80, v27
	v_xad_u32 v31, v31, v28, 0
	v_add_u32_e32 v28, 0x400, v28
	s_waitcnt vmcnt(15) lgkmcnt(0)
	v_mfma_f32_32x32x16_bf16 v[2:17], v[32:35], v[94:97], v[2:17]
	global_load_dwordx4 v[94:97], v[114:115], off offset:3072
	v_lshl_add_u64 v[114:115], v[114:115], 0, s[98:99]
	v_and_b32_e32 v32, 0x70, v27
	v_xad_u32 v33, v32, v18, v31
	ds_read_b128 v[34:37], v33
	v_xad_u32 v33, v32, v24, v31
	v_add_u32_e32 v27, 8, v27
	s_waitcnt vmcnt(15) lgkmcnt(0)
	v_mfma_f32_32x32x16_bf16 v[2:17], v[34:37], v[98:101], v[2:17]
	global_load_dwordx4 v[98:101], v[114:115], off
	ds_read_b128 v[34:37], v33
	v_xad_u32 v33, v32, v25, v31
	v_xad_u32 v31, v32, v26, v31
	s_waitcnt vmcnt(15) lgkmcnt(0)
	v_mfma_f32_32x32x16_bf16 v[2:17], v[34:37], v[102:105], v[2:17]
	global_load_dwordx4 v[102:105], v[114:115], off offset:1024
	ds_read_b128 v[34:37], v33
	s_waitcnt vmcnt(15) lgkmcnt(0)
	v_mfma_f32_32x32x16_bf16 v[2:17], v[34:37], v[106:109], v[2:17]
	global_load_dwordx4 v[106:109], v[114:115], off offset:2048
	ds_read_b128 v[32:35], v31
	s_waitcnt vmcnt(15) lgkmcnt(0)
	v_mfma_f32_32x32x16_bf16 v[2:17], v[32:35], v[110:113], v[2:17]
	global_load_dwordx4 v[110:113], v[114:115], off offset:3072
	v_lshl_add_u64 v[114:115], v[114:115], 0, s[98:99]
	s_branch .Lcmp_end
; #define LAS __attribute__((address_space(3)))
; #define MFMA32(a, b, c) __builtin_amdgcn_mfma_f32_32x32x16_bf16((a), (b), (c), 0, 0, 0)
; __device__ __forceinline__ void compress_item(const CmpArgs& A, int item, LAS unsigned char* lds, int tid) {
;     ...
; #pragma unroll 8
;     for (int pos = 0; pos < 32; ++pos) { const int t = 16 * r + pos; LAS const unsigned char* arow = lds + (t ^ ((t >> 7) & 1)) * 128; const int sw = (t >> 4) & 7;
; #pragma unroll
;         for (int q = 0; q < 4; ++q) { const bf16x8 af = *(LAS const bf16x8*)(arow + (((2 * q + hh) ^ sw) * 16)), bfr = *(const bf16x8*)(wf + (size_t)(4 * pos + q) * 512); acc = MFMA32(af, bfr, acc); } }
;     __syncthreads();
;     { const float bias = A.cb[kv * 256 + 32 * w + r];
; #pragma unroll
;       for (int i = 0; i < 16; ++i) { const float x = acc[i] + bias; const float hv = 0.5f * x * (1.f + tanhf(0.7978845608028654f * (x + 0.044715f * x * x * x)));
.Lcmp_tail:
	v_bitop3_b32 v34, v33, v18, s35 bitop3:0x6c
	v_or_b32_e32 v34, v34, v32
	v_add_u32_e32 v34, 0, v34
	v_add3_u32 v34, v34, v28, s11
	ds_read_b128 v[34:37], v34
	s_waitcnt vmcnt(15) lgkmcnt(0)
	v_mfma_f32_32x32x16_bf16 v[2:17], v[34:37], v[50:53], v[2:17]
	v_bitop3_b32 v34, v33, v24, s35 bitop3:0x6c
	v_or_b32_e32 v34, v34, v32
	v_add_u32_e32 v34, 0, v34
	v_add3_u32 v34, v34, v28, s11
	ds_read_b128 v[34:37], v34
	s_waitcnt vmcnt(14) lgkmcnt(0)
	v_mfma_f32_32x32x16_bf16 v[2:17], v[34:37], v[54:57], v[2:17]
	v_bitop3_b32 v34, v33, v25, s35 bitop3:0x6c
	v_or_b32_e32 v34, v34, v32
	v_add_u32_e32 v34, 0, v34
	v_add3_u32 v34, v34, v28, s11
	ds_read_b128 v[34:37], v34
	v_bitop3_b32 v33, v33, v26, s35 bitop3:0x6c
	v_or_b32_e32 v32, v33, v32
	v_add_u32_e32 v32, 0, v32
	v_add3_u32 v32, v32, v28, s11
	s_waitcnt vmcnt(13) lgkmcnt(0)
	v_mfma_f32_32x32x16_bf16 v[2:17], v[34:37], v[58:61], v[2:17]
	ds_read_b128 v[32:35], v32
	v_add_u32_e32 v44, -1, v27
	s_waitcnt vmcnt(12) lgkmcnt(0)
	v_mfma_f32_32x32x16_bf16 v[2:17], v[32:35], v[62:65], v[2:17]
	v_add_u32_e32 v32, -2, v27
	v_add_u32_e32 v33, 0xffffff00, v28
	v_and_b32_e32 v34, 0x80, v32
	v_xad_u32 v36, v34, v33, 0
	v_and_b32_e32 v37, 0x70, v32
	v_xad_u32 v32, v37, v18, v36
	ds_read_b128 v[32:35], v32
	s_waitcnt vmcnt(11) lgkmcnt(0)
	v_mfma_f32_32x32x16_bf16 v[2:17], v[32:35], v[66:69], v[2:17]
	v_xad_u32 v32, v37, v24, v36
	ds_read_b128 v[32:35], v32
	s_waitcnt vmcnt(10) lgkmcnt(0)
	v_mfma_f32_32x32x16_bf16 v[2:17], v[32:35], v[70:73], v[2:17]
	v_xad_u32 v32, v37, v25, v36
	ds_read_b128 v[32:35], v32
	s_waitcnt vmcnt(9) lgkmcnt(0)
	v_mfma_f32_32x32x16_bf16 v[2:17], v[32:35], v[74:77], v[2:17]
	v_xad_u32 v32, v37, v26, v36
	ds_read_b128 v[32:35], v32
	s_nop 0
	s_waitcnt vmcnt(8) lgkmcnt(0)
	v_mfma_f32_32x32x16_bf16 v[2:17], v[32:35], v[78:81], v[2:17]
	v_bitop3_b32 v32, v44, v18, s35 bitop3:0x6c
	v_or_b32_e32 v32, v32, v31
	v_add_u32_e32 v32, 0, v32
	v_add3_u32 v32, v32, v28, s3
	ds_read_b128 v[32:35], v32
	s_waitcnt vmcnt(7) lgkmcnt(0)
	v_mfma_f32_32x32x16_bf16 v[2:17], v[32:35], v[82:85], v[2:17]
	v_bitop3_b32 v32, v44, v24, s35 bitop3:0x6c
	v_or_b32_e32 v32, v32, v31
	v_add_u32_e32 v32, 0, v32
	v_add3_u32 v32, v32, v28, s3
	ds_read_b128 v[32:35], v32
	s_waitcnt vmcnt(6) lgkmcnt(0)
	v_mfma_f32_32x32x16_bf16 v[2:17], v[32:35], v[86:89], v[2:17]
	v_bitop3_b32 v32, v44, v25, s35 bitop3:0x6c
	v_or_b32_e32 v32, v32, v31
	v_add_u32_e32 v32, 0, v32
	v_add3_u32 v32, v32, v28, s3
	ds_read_b128 v[32:35], v32
	s_waitcnt vmcnt(5) lgkmcnt(0)
	v_mfma_f32_32x32x16_bf16 v[2:17], v[32:35], v[90:93], v[2:17]
	v_bitop3_b32 v32, v44, v26, s35 bitop3:0x6c
	v_or_b32_e32 v31, v32, v31
	v_add_u32_e32 v31, 0, v31
	v_add3_u32 v31, v31, v28, s3
	ds_read_b128 v[32:35], v31
	v_and_b32_e32 v31, 0x80, v27
	v_xad_u32 v31, v31, v28, 0
	v_add_u32_e32 v28, 0x400, v28
	s_waitcnt vmcnt(4) lgkmcnt(0)
	v_mfma_f32_32x32x16_bf16 v[2:17], v[32:35], v[94:97], v[2:17]
	v_and_b32_e32 v32, 0x70, v27
	v_xad_u32 v33, v32, v18, v31
	ds_read_b128 v[34:37], v33
	v_xad_u32 v33, v32, v24, v31
	v_add_u32_e32 v27, 8, v27
	s_waitcnt vmcnt(3) lgkmcnt(0)
	v_mfma_f32_32x32x16_bf16 v[2:17], v[34:37], v[98:101], v[2:17]
	ds_read_b128 v[34:37], v33
	v_xad_u32 v33, v32, v25, v31
	v_xad_u32 v31, v32, v26, v31
	s_waitcnt vmcnt(2) lgkmcnt(0)
	v_mfma_f32_32x32x16_bf16 v[2:17], v[34:37], v[102:105], v[2:17]
	ds_read_b128 v[34:37], v33
	s_waitcnt vmcnt(1) lgkmcnt(0)
	v_mfma_f32_32x32x16_bf16 v[2:17], v[34:37], v[106:109], v[2:17]
	ds_read_b128 v[32:35], v31
	s_waitcnt vmcnt(0) lgkmcnt(0)
	v_mfma_f32_32x32x16_bf16 v[2:17], v[32:35], v[110:113], v[2:17]
.Lcmp_end:
	s_cmp_eq_u32 s40, 0x20000
	s_cbranch_scc0 .LBB0_930
	s_lshl_b32 s9, s0, 8
	s_lshl_b32 s12, s8, 5
	s_add_i32 s8, s12, s9
	v_or_b32_e32 v20, s8, v38
	v_readlane_b32 s8, v255, 0
	v_ashrrev_i32_e32 v21, 31, v20
	v_readlane_b32 s9, v255, 1
	s_barrier
	s_nop 0
	v_lshl_add_u64 v[20:21], v[20:21], 2, s[8:9]
	global_load_dword v0, v[20:21], off
	s_waitcnt vmcnt(0)
	v_add_f32_e32 v19, v2, v0
	v_mul_f32_e32 v2, 0x3d372713, v19
	v_mul_f32_e32 v2, v19, v2
	v_fma_f32 v2, v19, v2, v19
	v_mul_f32_e32 v20, 0x3f4c422a, v2
	v_cmp_nlt_f32_e64 s[8:9], |v20|, s30
	s_and_saveexec_b64 s[24:25], s[8:9]
	s_xor_b64 s[8:9], exec, s[24:25]
	s_cbranch_execz .LBB0_933
	v_add_f32_e64 v2, |v20|, |v20|
	v_mul_f32_e32 v21, 0x3fb8aa3b, v2
	v_rndne_f32_e32 v22, v21
	v_sub_f32_e32 v23, v21, v22
	v_fma_f32 v21, v2, s19, -v21
	v_fmac_f32_e32 v21, 0x32a5705f, v2
	v_add_f32_e32 v21, v23, v21
	v_cvt_i32_f32_e32 v22, v22
	v_exp_f32_e32 v21, v21
	v_cmp_ngt_f32_e32 vcc, s73, v2
	v_ldexp_f32 v21, v21, v22
	s_nop 0
	v_cndmask_b32_e32 v21, 0, v21, vcc
	v_cmp_nlt_f32_e32 vcc, s74, v2
	s_nop 1
	v_cndmask_b32_e32 v2, v217, v21, vcc
	v_add_f32_e32 v2, 1.0, v2
	v_rcp_f32_e32 v2, v2
	s_nop 0
	v_fma_f32 v21, v2, -2.0, 1.0
